# scan: FLUSH prelude (operand reads + store address) executed only by waves 4-7
# baseline (speedup 1.0000x reference)
.LBB0_395:
.Lsx0_c:
	s_and_saveexec_b64 s[2:3], s[56:57]
	s_cbranch_execz .LBB0_403
	s_cmp_lg_u32 s21, 0
	s_cbranch_scc0 .Lsx0_a
	s_add_i32 s24, s21, -16
	s_and_b64 s[98:99], s[12:13], exec
	s_cselect_b32 s98, s24, s19
	ds_read_b64 v[236:237], v190 offset:4096
	ds_read_b64 v[234:235], v244 offset:4096
	v_lshl_add_u32 v194, s98, 6, v183
	v_lshl_add_u64 v[238:239], v[194:195], 1, s[78:79]
.Lsx0_a:
	ds_read_b128 v[48:51], v174
	ds_read_b128 v[60:63], v192 offset:49152
	ds_read_b128 v[52:55], v174 offset:64
	ds_read_b128 v[64:67], v192 offset:49216
	ds_read_b128 v[56:59], v175
	ds_read_b128 v[68:71], v199
	ds_read_b128 v[72:75], v192 offset:58368
	ds_read_b128 v[76:79], v192 offset:58432
	ds_read_b128 v[80:83], v151
	ds_read_b128 v[84:87], v151 offset:16
	ds_read_b128 v[88:91], v151 offset:32
	ds_read_b128 v[92:95], v151 offset:48
	s_waitcnt lgkmcnt(10)
	v_mfma_f32_16x16x32_bf16 v[30:33], v[48:51], v[60:63], 0
	s_waitcnt lgkmcnt(8)
	v_mfma_f32_16x16x32_bf16 v[30:33], v[52:55], v[64:67], v[30:33]
	s_waitcnt lgkmcnt(6)
	v_mfma_f32_16x16x32_bf16 v[30:33], v[56:59], v[68:71], v[30:33]
	s_waitcnt lgkmcnt(5)
	v_mfma_f32_16x16x32_bf16 v[22:25], v[48:51], v[72:75], 0
	s_waitcnt lgkmcnt(4)
	v_mfma_f32_16x16x32_bf16 v[22:25], v[52:55], v[76:79], v[22:25]
	s_cmp_eq_u32 s36, 0
	s_cbranch_scc1 .Lis0b
	s_cmp_gt_u32 s36, 62
	s_cbranch_scc1 .Lis0b
	s_add_i32 s24, s19, 0xffffffc0
	s_add_i32 s25, s21, 0x30
	s_and_b64 s[98:99], s[12:13], exec
	s_cselect_b32 s24, s25, s24
	v_lshl_add_u32 v194, s24, 6, v183
	v_lshlrev_b32_e32 v112, 1, v194
	global_load_dword v5, v112, s[44:45]
	global_load_dword v207, v112, s[44:45] offset:-1024
	global_load_dword v6, v112, s[42:43]
	global_load_dword v208, v112, s[42:43] offset:-1024
	global_load_dword v7, v112, s[0:1]
	global_load_dword v209, v112, s[0:1] offset:-1024
	global_load_dword v8, v112, s[34:35]
	global_load_dword v210, v112, s[34:35] offset:-1024
	global_load_dword v9, v112, s[76:77]
	global_load_dword v211, v112, s[76:77] offset:-1024
	v_add_u32_e32 v194, s24, v184
	v_lshlrev_b32_e32 v114, 2, v194
	global_load_dword v110, v114, s[40:41]
	global_load_dword v212, v114, s[40:41] offset:-32

.LBB0_424:
.LBB0_426:
	s_add_i32 s24, s19, -16
	s_and_b64 s[2:3], s[12:13], exec
	s_waitcnt lgkmcnt(0)
	s_barrier
	s_cselect_b32 s2, s21, s24
	s_mov_b32 s99, s2
	s_cmpk_lt_u32 s20, 0x7f
	s_cselect_b64 s[2:3], -1, 0
	s_and_b64 s[68:69], s[54:55], s[2:3]
.Lsx1_c:
	s_and_saveexec_b64 s[74:75], s[56:57]
	s_cbranch_execz .LBB0_432
	ds_read_b64 v[236:237], v190
	ds_read_b64 v[234:235], v244
	v_lshl_add_u32 v194, s99, 6, v183
	v_lshl_add_u64 v[238:239], v[194:195], 1, s[78:79]
	ds_read_b128 v[48:51], v174
	ds_read_b128 v[60:63], v192 offset:51456
	ds_read_b128 v[52:55], v174 offset:64
	ds_read_b128 v[64:67], v192 offset:51520
	ds_read_b128 v[56:59], v175 offset:5120
	ds_read_b128 v[68:71], v199
	ds_read_b128 v[72:75], v192 offset:60672
	ds_read_b128 v[76:79], v192 offset:60736
	ds_read_b128 v[80:83], v151
	ds_read_b128 v[84:87], v151 offset:16
	ds_read_b128 v[88:91], v151 offset:32
	ds_read_b128 v[92:95], v151 offset:48
	s_waitcnt lgkmcnt(10)
	v_mfma_f32_16x16x32_bf16 v[30:33], v[48:51], v[60:63], 0
	s_waitcnt lgkmcnt(8)
	v_mfma_f32_16x16x32_bf16 v[30:33], v[52:55], v[64:67], v[30:33]
	s_waitcnt lgkmcnt(6)
	v_mfma_f32_16x16x32_bf16 v[30:33], v[56:59], v[68:71], v[30:33]
	s_waitcnt lgkmcnt(5)
	v_mfma_f32_16x16x32_bf16 v[22:25], v[48:51], v[72:75], 0
	s_waitcnt lgkmcnt(4)
	v_mfma_f32_16x16x32_bf16 v[22:25], v[52:55], v[76:79], v[22:25]
	s_cmp_gt_u32 s36, 61
	s_cbranch_scc1 .Lis1bw
	s_add_i32 s24, s19, 0xffffffb0
	s_add_i32 s25, s21, 64
	s_and_b64 s[98:99], s[12:13], exec
	s_cselect_b32 s24, s25, s24
	v_lshl_add_u32 v194, s24, 6, v183
	v_lshlrev_b32_e32 v112, 1, v194
	global_load_dword v0, v112, s[44:45]
	global_load_dword v201, v112, s[44:45] offset:-1024
	global_load_dword v1, v112, s[42:43]
	global_load_dword v202, v112, s[42:43] offset:-1024
	global_load_dword v2, v112, s[0:1]
	global_load_dword v203, v112, s[0:1] offset:-1024
	global_load_dword v4, v112, s[76:77]
	global_load_dword v205, v112, s[76:77] offset:-1024
	global_load_dword v3, v112, s[34:35]
	global_load_dword v204, v112, s[34:35] offset:-1024
	v_add_u32_e32 v194, s24, v184
	v_lshlrev_b32_e32 v114, 2, v194
	global_load_dword v108, v114, s[40:41]
	global_load_dword v206, v114, s[40:41] offset:-32
	s_branch .Lis1b
